# P1: accumulator zeroing pass removed (first K-iteration peeled, first MFMA per accumulator quad takes C=0)
# speedup vs baseline: 1.0065x; 1.0065x over previous
; #define PG8_LAS __attribute__((address_space(3)))
; #define PG8_WAIT_V(n) asm volatile("s_waitcnt vmcnt(" #n ")" ::: "memory")
; #define PG8_BAR __builtin_amdgcn_s_barrier()
; template <class Epi, class Sched, bool ALIGN_EPI = false, bool SP2 = false, bool RS = false, bool BPRE = false>
; __device__ __forceinline__ void gemm_phase(PG8_LAS unsigned char* lds, const Gemm g, const Sched& S, const Epi& E, const float* rs_ss = nullptr, PG8_LAS float* rs_tab = nullptr) {
;     ...
;         const bool has_next = S.next(ui + 1, nxt);
;         const char* nA = has_next ? (const char*)g.A + (size_t)nxt.pm * tstep : cA; const char* nB = has_next ? (const char*)g.Bt + (size_t)nxt.pn * tstep : cB;
;         for (int t = 0; t < nt; t += 2) {
;             const bool last = (t == nt - 2);
;             if constexpr (RS) { if (t == 16 || t == 32) { const PG8_LAS float* tp = rs_tab + (ui & 1) * 768 + (t == 32 ? 256 : 0);
;                 _Pragma("unroll") for (int a = 0; a < 2; ++a) _Pragma("unroll") for (int m = 0; m < 4; ++m) { const float f = tp[a * HALF + wr * 64 + m * 16 + fr];
;                     _Pragma("unroll") for (int b = 0; b < 2; ++b) _Pragma("unroll") for (int n = 0; n < 2; ++n) acc[a][b][m][n] = acc[a][b][m][n] * f; } } }
;             const char* a1 = cA + (size_t)(t + 1) * kstep;
;             const char* a2 = last ? nA : cA + (size_t)(t + 2) * kstep; const char* b2 = last ? nB : cB + (size_t)(t + 2) * kstep;
;             const char* a3 = a2 + kstep; const char* b3 = b2 + kstep;
;             if (last && has_next) S.a_ready(nxt);
;             if constexpr (SP2) {
;             PG8_LDB(B0, 0, 0); PG8_LDB(B1, 0, 1); PG8_SCHED; PG8_LDA(At, 0, 0); PG8_STAGE(PG8_SA(1, 1), a1 + hstep, voffA);
;             PG8_WAIT_V(8); PG8_WAIT_L(0); PG8_BAR; PG8_MMA(0, 0, At, B0); PG8_MMA(0, 1, At, B1); PG8_BAR; PG8_SCHED;
;             PG8_LDA(At, 0, 1); PG8_STAGE(PG8_SB(0, 0), b2, voffB); PG8_STAGE(PG8_SB(0, 1), b2 + hstep, voffB); PG8_STAGE(PG8_SA(0, 0), a2, voffA);
;             PG8_WAIT_V(8); PG8_WAIT_L(0); PG8_BAR; PG8_MMA(1, 0, At, B0); PG8_MMA(1, 1, At, B1); PG8_BAR; PG8_SCHED;
;     ...
; #pragma unroll
;         for (int a = 0; a < 2; ++a)
; #pragma unroll
;             for (int b = 0; b < 2; ++b)
; #pragma unroll
;                 for (int m = 0; m < 4; ++m)
; #pragma unroll
;                     for (int n = 0; n < 2; ++n) acc[a][b][m][n] = (f32x4){0.f, 0.f, 0.f, 0.f};
.LBB0_195:
	s_ashr_i32 s19, s18, 31
	s_lshl_b64 s[20:21], s[18:19], 20
	s_add_u32 s20, s30, s20
	s_addc_u32 s21, s31, s21
	s_and_b64 s[44:45], s[6:7], exec
	s_cselect_b32 s5, s21, s57
	s_cselect_b32 s19, s20, s56
	s_ashr_i32 s17, s16, 31
	s_lshl_b64 s[44:45], s[16:17], 20
	s_add_u32 s44, s24, s44
	s_addc_u32 s45, s25, s45
	s_and_b64 s[60:61], s[6:7], exec
	s_cselect_b32 s17, s45, s59
	s_cselect_b32 s47, s44, s58
	s_add_u32 s56, s56, 0x84000
	s_addc_u32 s57, s57, 0
	s_add_u32 s87, s58, 0x8000
	s_addc_u32 s88, s59, 0
	s_mov_b32 s89, -2
	s_waitcnt lgkmcnt(0)
	ds_read_b128 v[130:133], v161
	ds_read_b128 v[134:137], v161 offset:1024
	ds_read_b128 v[152:155], v161 offset:2048
	ds_read_b128 v[156:159], v161 offset:3072
	ds_read_b128 v[166:169], v162
	ds_read_b128 v[170:173], v162 offset:1024
	ds_read_b128 v[174:177], v162 offset:2048
	ds_read_b128 v[182:185], v162 offset:3072
	s_add_u32 s58, s56, 0xfff84000
	s_addc_u32 s59, s57, -1
	s_cmp_eq_u32 s89, 28
	s_cselect_b32 s70, s19, s58
	s_cselect_b32 s71, s5, s59
	s_cselect_b32 s60, s47, s87
	s_cselect_b32 s61, s17, s88
	s_add_u32 s58, s70, 0x4000
	s_addc_u32 s59, s71, 0
	v_lshl_add_u64 v[178:179], s[56:57], 0, v[138:139]
	s_add_i32 m0, s72, 0xc000
	ds_read_b128 v[186:189], v163
	ds_read_b128 v[190:193], v163 offset:1024
	ds_read_b128 v[194:197], v163 offset:2048
	ds_read_b128 v[198:201], v163 offset:3072
	ds_read_b128 v[202:205], v163 offset:4096
	ds_read_b128 v[206:209], v163 offset:5120
	ds_read_b128 v[210:213], v163 offset:6144
	ds_read_b128 v[214:217], v163 offset:7168
	global_load_lds_dwordx4 v[178:179], off
	v_lshl_add_u64 v[178:179], s[56:57], 0, v[146:147]
	s_add_i32 m0, s72, 0xe000
	s_nop 0
	global_load_lds_dwordx4 v[178:179], off
	s_waitcnt vmcnt(8)
	s_waitcnt lgkmcnt(0)
	s_barrier
	s_setprio 1
	s_waitcnt lgkmcnt(0)
	v_mfma_f32_16x16x32_bf16 v[126:129], v[130:133], v[186:189], 0
	v_mfma_f32_16x16x32_bf16 v[122:125], v[152:155], v[186:189], 0
	v_mfma_f32_16x16x32_bf16 v[110:113], v[130:133], v[194:197], 0
	v_mfma_f32_16x16x32_bf16 v[106:109], v[152:155], v[194:197], 0
	v_mfma_f32_16x16x32_bf16 v[94:97], v[130:133], v[202:205], 0
	v_mfma_f32_16x16x32_bf16 v[90:93], v[152:155], v[202:205], 0
	v_mfma_f32_16x16x32_bf16 v[78:81], v[130:133], v[210:213], 0
	v_mfma_f32_16x16x32_bf16 v[74:77], v[152:155], v[210:213], 0
	v_mfma_f32_16x16x32_bf16 v[126:129], v[134:137], v[190:193], v[126:129]
	v_mfma_f32_16x16x32_bf16 v[122:125], v[156:159], v[190:193], v[122:125]
	v_mfma_f32_16x16x32_bf16 v[110:113], v[134:137], v[198:201], v[110:113]
	v_mfma_f32_16x16x32_bf16 v[106:109], v[156:159], v[198:201], v[106:109]
	v_mfma_f32_16x16x32_bf16 v[94:97], v[134:137], v[206:209], v[94:97]
	v_mfma_f32_16x16x32_bf16 v[90:93], v[156:159], v[206:209], v[90:93]
	v_mfma_f32_16x16x32_bf16 v[78:81], v[134:137], v[214:217], v[78:81]
	v_mfma_f32_16x16x32_bf16 v[74:77], v[156:159], v[214:217], v[74:77]
	s_setprio 0
	s_setprio 1
	v_mfma_f32_16x16x32_bf16 v[118:121], v[166:169], v[186:189], 0
	v_mfma_f32_16x16x32_bf16 v[114:117], v[174:177], v[186:189], 0
	v_mfma_f32_16x16x32_bf16 v[102:105], v[166:169], v[194:197], 0
	v_mfma_f32_16x16x32_bf16 v[98:101], v[174:177], v[194:197], 0
	v_mfma_f32_16x16x32_bf16 v[86:89], v[166:169], v[202:205], 0
	v_mfma_f32_16x16x32_bf16 v[82:85], v[174:177], v[202:205], 0
	v_mfma_f32_16x16x32_bf16 v[70:73], v[166:169], v[210:213], 0
	v_mfma_f32_16x16x32_bf16 v[66:69], v[174:177], v[210:213], 0
	v_mfma_f32_16x16x32_bf16 v[118:121], v[170:173], v[190:193], v[118:121]
	v_mfma_f32_16x16x32_bf16 v[114:117], v[182:185], v[190:193], v[114:117]
	v_mfma_f32_16x16x32_bf16 v[102:105], v[170:173], v[198:201], v[102:105]
	v_mfma_f32_16x16x32_bf16 v[98:101], v[182:185], v[198:201], v[98:101]
	v_mfma_f32_16x16x32_bf16 v[86:89], v[170:173], v[206:209], v[86:89]
	v_mfma_f32_16x16x32_bf16 v[82:85], v[182:185], v[206:209], v[82:85]
	v_mfma_f32_16x16x32_bf16 v[70:73], v[170:173], v[214:217], v[70:73]
	v_mfma_f32_16x16x32_bf16 v[66:69], v[182:185], v[214:217], v[66:69]
	s_setprio 0
	s_barrier
	s_add_i32 s90, s83, s15
	v_lshl_add_u64 v[178:179], s[60:61], 0, v[138:139]
	s_mov_b32 m0, s90
	ds_read_b128 v[186:189], v163 offset:16384
	ds_read_b128 v[190:193], v163 offset:17408
	ds_read_b128 v[194:197], v163 offset:18432
	ds_read_b128 v[198:201], v163 offset:19456
	ds_read_b128 v[202:205], v163 offset:20480
	ds_read_b128 v[206:209], v163 offset:21504
	ds_read_b128 v[210:213], v163 offset:22528
	ds_read_b128 v[214:217], v163 offset:23552
	global_load_lds_dwordx4 v[178:179], off
	s_add_i32 m0, s90, 0x2000
	s_add_u32 s90, s60, 0x80000
	v_lshl_add_u64 v[178:179], s[60:61], 0, v[140:141]
	s_addc_u32 s91, s61, 0
	s_add_i32 s92, s86, s15
	global_load_lds_dwordx4 v[178:179], off
	v_lshl_add_u64 v[178:179], s[90:91], 0, v[138:139]
	s_mov_b32 m0, s92
	s_nop 0
	global_load_lds_dwordx4 v[178:179], off
	v_lshl_add_u64 v[178:179], s[90:91], 0, v[140:141]
	s_add_i32 m0, s92, 0x2000
	s_nop 0
	global_load_lds_dwordx4 v[178:179], off
	v_lshl_add_u64 v[178:179], s[70:71], 0, v[138:139]
	s_mov_b32 m0, s72
	s_nop 0
	global_load_lds_dwordx4 v[178:179], off
	v_lshl_add_u64 v[178:179], s[70:71], 0, v[140:141]
	s_mov_b32 m0, s73
	s_nop 0
	global_load_lds_dwordx4 v[178:179], off
	s_waitcnt vmcnt(8)
	s_waitcnt lgkmcnt(0)
	s_barrier
; #define PG8_STAGE(bufoff, gbase, voff) do { _Pragma("unroll") for (int _i = 0; _i < 2; ++_i) \
;         __builtin_amdgcn_global_load_lds((const unsigned*)((const char*)(gbase) + (voff)[_i]), (PG8_LAS unsigned*)(lds + (bufoff) + ldsw + _i * 8192), 16, 0, 0); } while (0)
; #define PG8_LDA(dst, b, h) do { _Pragma("unroll") for (int m = 0; m < 4; ++m) _Pragma("unroll") for (int k = 0; k < 2; ++k) dst[m][k] = *(const PG8_LAS bf16x8*)(lds + PG8_SA(b, h) + aoff + m * 2048 + k * 1024); } while (0)
; #define PG8_LDB(dst, b, h) do { _Pragma("unroll") for (int n = 0; n < 2; ++n) _Pragma("unroll") for (int k = 0; k < 2; ++k) dst[n][k] = *(const PG8_LAS bf16x8*)(lds + PG8_SB(b, h) + boff + n * 2048 + k * 1024); } while (0)
; #define PG8_MMA(ai, bj, At, Bt) do { __builtin_amdgcn_s_setprio(1); _Pragma("unroll") for (int m = 0; m < 4; ++m) _Pragma("unroll") for (int n = 0; n < 2; ++n) _Pragma("unroll") for (int k = 0; k < 2; ++k) \
;         acc[ai][bj][m][n] = __builtin_amdgcn_mfma_f32_16x16x32_bf16(Bt[n][k], At[m][k], acc[ai][bj][m][n], 0, 0, 0); __builtin_amdgcn_s_setprio(0); } while (0)
; #define PG8_WAIT_V(n) asm volatile("s_waitcnt vmcnt(" #n ")" ::: "memory")
; #define PG8_WAIT_L(n) asm volatile("s_waitcnt lgkmcnt(" #n ")" ::: "memory")
; #define PG8_BAR __builtin_amdgcn_s_barrier()
; #define PG8_SCHED __builtin_amdgcn_sched_barrier(0)
; template <class Epi, class Sched, bool ALIGN_EPI = false, bool SP2 = false, bool RS = false, bool BPRE = false>
; __device__ __forceinline__ void gemm_phase(PG8_LAS unsigned char* lds, const Gemm g, const Sched& S, const Epi& E, const float* rs_ss = nullptr, PG8_LAS float* rs_tab = nullptr) {
;     ...
;             PG8_WAIT_V(8); PG8_WAIT_L(0); PG8_BAR; PG8_MMA(0, 0, At, B0); PG8_MMA(0, 1, At, B1); PG8_BAR; PG8_SCHED;
;             PG8_LDA(At, 0, 1); PG8_STAGE(PG8_SB(0, 0), b2, voffB); PG8_STAGE(PG8_SB(0, 1), b2 + hstep, voffB); PG8_STAGE(PG8_SA(0, 0), a2, voffA);
;             PG8_WAIT_V(8); PG8_WAIT_L(0); PG8_BAR; PG8_MMA(1, 0, At, B0); PG8_MMA(1, 1, At, B1); PG8_BAR; PG8_SCHED;
;             PG8_LDB(B0, 1, 0); PG8_LDB(B1, 1, 1); PG8_SCHED; PG8_LDA(At, 1, 0); PG8_STAGE(PG8_SA(0, 1), a2 + hstep, voffA);
;             PG8_WAIT_V(8); PG8_WAIT_L(0); PG8_BAR; PG8_MMA(0, 0, At, B0); PG8_MMA(0, 1, At, B1); PG8_BAR; PG8_SCHED;
	s_setprio 1
	s_waitcnt lgkmcnt(0)
	v_mfma_f32_16x16x32_bf16 v[62:65], v[130:133], v[186:189], 0
	v_mfma_f32_16x16x32_bf16 v[58:61], v[152:155], v[186:189], 0
	v_mfma_f32_16x16x32_bf16 v[46:49], v[130:133], v[194:197], 0
	v_mfma_f32_16x16x32_bf16 v[42:45], v[152:155], v[194:197], 0
	v_mfma_f32_16x16x32_bf16 v[30:33], v[130:133], v[202:205], 0
	v_mfma_f32_16x16x32_bf16 v[26:29], v[152:155], v[202:205], 0
	v_mfma_f32_16x16x32_bf16 v[14:17], v[130:133], v[210:213], 0
	v_mfma_f32_16x16x32_bf16 v[10:13], v[152:155], v[210:213], 0
	v_mfma_f32_16x16x32_bf16 v[62:65], v[134:137], v[190:193], v[62:65]
	v_mfma_f32_16x16x32_bf16 v[58:61], v[156:159], v[190:193], v[58:61]
	v_mfma_f32_16x16x32_bf16 v[46:49], v[134:137], v[198:201], v[46:49]
	v_mfma_f32_16x16x32_bf16 v[42:45], v[156:159], v[198:201], v[42:45]
	v_mfma_f32_16x16x32_bf16 v[30:33], v[134:137], v[206:209], v[30:33]
	v_mfma_f32_16x16x32_bf16 v[26:29], v[156:159], v[206:209], v[26:29]
	v_mfma_f32_16x16x32_bf16 v[14:17], v[134:137], v[214:217], v[14:17]
	v_mfma_f32_16x16x32_bf16 v[10:13], v[156:159], v[214:217], v[10:13]
	s_setprio 0
	s_setprio 1
	v_mfma_f32_16x16x32_bf16 v[54:57], v[166:169], v[186:189], 0
	v_mfma_f32_16x16x32_bf16 v[50:53], v[174:177], v[186:189], 0
	v_mfma_f32_16x16x32_bf16 v[38:41], v[166:169], v[194:197], 0
	v_mfma_f32_16x16x32_bf16 v[34:37], v[174:177], v[194:197], 0
	v_mfma_f32_16x16x32_bf16 v[22:25], v[166:169], v[202:205], 0
	v_mfma_f32_16x16x32_bf16 v[18:21], v[174:177], v[202:205], 0
	v_mfma_f32_16x16x32_bf16 v[6:9], v[166:169], v[210:213], 0
	v_mfma_f32_16x16x32_bf16 v[2:5], v[174:177], v[210:213], 0
	v_mfma_f32_16x16x32_bf16 v[54:57], v[170:173], v[190:193], v[54:57]
	v_mfma_f32_16x16x32_bf16 v[50:53], v[182:185], v[190:193], v[50:53]
	v_mfma_f32_16x16x32_bf16 v[38:41], v[170:173], v[198:201], v[38:41]
	v_mfma_f32_16x16x32_bf16 v[34:37], v[182:185], v[198:201], v[34:37]
	v_mfma_f32_16x16x32_bf16 v[22:25], v[170:173], v[206:209], v[22:25]
	v_mfma_f32_16x16x32_bf16 v[18:21], v[182:185], v[206:209], v[18:21]
	v_mfma_f32_16x16x32_bf16 v[6:9], v[170:173], v[214:217], v[6:9]
	v_mfma_f32_16x16x32_bf16 v[2:5], v[182:185], v[214:217], v[2:5]
	s_setprio 0
	s_barrier
	s_add_i32 s90, 0, 0x18000
	v_add_u32_e32 v143, s90, v160
	s_add_i32 s91, 0, 0x1c000
	ds_read_b128 v[130:133], v143
	ds_read_b128 v[134:137], v143 offset:1024
	ds_read_b128 v[152:155], v143 offset:2048
	ds_read_b128 v[156:159], v143 offset:3072
	v_add_u32_e32 v143, s91, v160
	ds_read_b128 v[166:169], v143
	ds_read_b128 v[170:173], v143 offset:1024
	ds_read_b128 v[174:177], v143 offset:2048
	ds_read_b128 v[182:185], v143 offset:3072
	s_add_u32 s70, s70, 0x80000
	s_addc_u32 s71, s71, 0
	s_mov_b32 m0, s74
	v_lshl_add_u64 v[178:179], s[70:71], 0, v[138:139]
	ds_read_b128 v[186:189], v163 offset:32768
	ds_read_b128 v[190:193], v163 offset:33792
	ds_read_b128 v[194:197], v163 offset:34816
	ds_read_b128 v[198:201], v163 offset:35840
	ds_read_b128 v[202:205], v163 offset:36864
	ds_read_b128 v[206:209], v163 offset:37888
	ds_read_b128 v[210:213], v163 offset:38912
	ds_read_b128 v[214:217], v163 offset:39936
	global_load_lds_dwordx4 v[178:179], off
	v_lshl_add_u64 v[178:179], s[70:71], 0, v[140:141]
	s_mov_b32 m0, s75
	s_nop 0
	global_load_lds_dwordx4 v[178:179], off
	s_waitcnt vmcnt(8)
	s_waitcnt lgkmcnt(0)
	s_barrier
	s_setprio 1
	s_waitcnt lgkmcnt(0)
	v_mfma_f32_16x16x32_bf16 v[126:129], v[130:133], v[186:189], v[126:129]
	v_mfma_f32_16x16x32_bf16 v[122:125], v[152:155], v[186:189], v[122:125]
	v_mfma_f32_16x16x32_bf16 v[110:113], v[130:133], v[194:197], v[110:113]
	v_mfma_f32_16x16x32_bf16 v[106:109], v[152:155], v[194:197], v[106:109]
	v_mfma_f32_16x16x32_bf16 v[94:97], v[130:133], v[202:205], v[94:97]
	v_mfma_f32_16x16x32_bf16 v[90:93], v[152:155], v[202:205], v[90:93]
	v_mfma_f32_16x16x32_bf16 v[78:81], v[130:133], v[210:213], v[78:81]
	v_mfma_f32_16x16x32_bf16 v[74:77], v[152:155], v[210:213], v[74:77]
	v_mfma_f32_16x16x32_bf16 v[126:129], v[134:137], v[190:193], v[126:129]
	v_mfma_f32_16x16x32_bf16 v[122:125], v[156:159], v[190:193], v[122:125]
	v_mfma_f32_16x16x32_bf16 v[110:113], v[134:137], v[198:201], v[110:113]
	v_mfma_f32_16x16x32_bf16 v[106:109], v[156:159], v[198:201], v[106:109]
	v_mfma_f32_16x16x32_bf16 v[94:97], v[134:137], v[206:209], v[94:97]
	v_mfma_f32_16x16x32_bf16 v[90:93], v[156:159], v[206:209], v[90:93]
	v_mfma_f32_16x16x32_bf16 v[78:81], v[134:137], v[214:217], v[78:81]
	v_mfma_f32_16x16x32_bf16 v[74:77], v[156:159], v[214:217], v[74:77]
	s_setprio 0
	s_setprio 1
	v_mfma_f32_16x16x32_bf16 v[118:121], v[166:169], v[186:189], v[118:121]
	v_mfma_f32_16x16x32_bf16 v[114:117], v[174:177], v[186:189], v[114:117]
	v_mfma_f32_16x16x32_bf16 v[102:105], v[166:169], v[194:197], v[102:105]
	v_mfma_f32_16x16x32_bf16 v[98:101], v[174:177], v[194:197], v[98:101]
	v_mfma_f32_16x16x32_bf16 v[86:89], v[166:169], v[202:205], v[86:89]
	v_mfma_f32_16x16x32_bf16 v[82:85], v[174:177], v[202:205], v[82:85]
	v_mfma_f32_16x16x32_bf16 v[70:73], v[166:169], v[210:213], v[70:73]
	v_mfma_f32_16x16x32_bf16 v[66:69], v[174:177], v[210:213], v[66:69]
	v_mfma_f32_16x16x32_bf16 v[118:121], v[170:173], v[190:193], v[118:121]
	v_mfma_f32_16x16x32_bf16 v[114:117], v[182:185], v[190:193], v[114:117]
	v_mfma_f32_16x16x32_bf16 v[102:105], v[170:173], v[198:201], v[102:105]
	v_mfma_f32_16x16x32_bf16 v[98:101], v[182:185], v[198:201], v[98:101]
	v_mfma_f32_16x16x32_bf16 v[86:89], v[170:173], v[206:209], v[86:89]
	v_mfma_f32_16x16x32_bf16 v[82:85], v[182:185], v[206:209], v[82:85]
	v_mfma_f32_16x16x32_bf16 v[70:73], v[170:173], v[214:217], v[70:73]
	v_mfma_f32_16x16x32_bf16 v[66:69], v[182:185], v[214:217], v[66:69]
	s_setprio 0
	s_barrier
; #define PG8_STAGE(bufoff, gbase, voff) do { _Pragma("unroll") for (int _i = 0; _i < 2; ++_i) \
;         __builtin_amdgcn_global_load_lds((const unsigned*)((const char*)(gbase) + (voff)[_i]), (PG8_LAS unsigned*)(lds + (bufoff) + ldsw + _i * 8192), 16, 0, 0); } while (0)
; #define PG8_LDA(dst, b, h) do { _Pragma("unroll") for (int m = 0; m < 4; ++m) _Pragma("unroll") for (int k = 0; k < 2; ++k) dst[m][k] = *(const PG8_LAS bf16x8*)(lds + PG8_SA(b, h) + aoff + m * 2048 + k * 1024); } while (0)
; #define PG8_LDB(dst, b, h) do { _Pragma("unroll") for (int n = 0; n < 2; ++n) _Pragma("unroll") for (int k = 0; k < 2; ++k) dst[n][k] = *(const PG8_LAS bf16x8*)(lds + PG8_SB(b, h) + boff + n * 2048 + k * 1024); } while (0)
; #define PG8_MMA(ai, bj, At, Bt) do { __builtin_amdgcn_s_setprio(1); _Pragma("unroll") for (int m = 0; m < 4; ++m) _Pragma("unroll") for (int n = 0; n < 2; ++n) _Pragma("unroll") for (int k = 0; k < 2; ++k) \
;         acc[ai][bj][m][n] = __builtin_amdgcn_mfma_f32_16x16x32_bf16(Bt[n][k], At[m][k], acc[ai][bj][m][n], 0, 0, 0); __builtin_amdgcn_s_setprio(0); } while (0)
; #define PG8_WAIT_V(n) asm volatile("s_waitcnt vmcnt(" #n ")" ::: "memory")
; #define PG8_WAIT_L(n) asm volatile("s_waitcnt lgkmcnt(" #n ")" ::: "memory")
; #define PG8_BAR __builtin_amdgcn_s_barrier()
; #define PG8_SCHED __builtin_amdgcn_sched_barrier(0)
; template <class Epi, class Sched, bool ALIGN_EPI = false, bool SP2 = false, bool RS = false, bool BPRE = false>
; __device__ __forceinline__ void gemm_phase(PG8_LAS unsigned char* lds, const Gemm g, const Sched& S, const Epi& E, const float* rs_ss = nullptr, PG8_LAS float* rs_tab = nullptr) {
;     ...
;             PG8_LDB(B0, 1, 0); PG8_LDB(B1, 1, 1); PG8_SCHED; PG8_LDA(At, 1, 0); PG8_STAGE(PG8_SA(0, 1), a2 + hstep, voffA);
;             PG8_WAIT_V(8); PG8_WAIT_L(0); PG8_BAR; PG8_MMA(0, 0, At, B0); PG8_MMA(0, 1, At, B1); PG8_BAR; PG8_SCHED;
;             PG8_LDA(At, 1, 1); PG8_STAGE(PG8_SB(1, 0), b3, voffB); PG8_STAGE(PG8_SB(1, 1), b3 + hstep, voffB); PG8_STAGE(PG8_SA(1, 0), a3, voffA);
;             PG8_WAIT_V(8); PG8_WAIT_L(0); PG8_BAR; PG8_MMA(1, 0, At, B0); PG8_MMA(1, 1, At, B1); PG8_BAR; PG8_SCHED;
	s_add_u32 s70, s60, 0x4000
	s_addc_u32 s71, s61, 0
	s_add_i32 s90, s90, s15
	v_lshl_add_u64 v[178:179], s[70:71], 0, v[138:139]
	s_mov_b32 m0, s90
	ds_read_b128 v[186:189], v163 offset:49152
	ds_read_b128 v[190:193], v163 offset:50176
	ds_read_b128 v[194:197], v163 offset:51200
	ds_read_b128 v[198:201], v163 offset:52224
	ds_read_b128 v[202:205], v163 offset:53248
	ds_read_b128 v[206:209], v163 offset:54272
	ds_read_b128 v[210:213], v163 offset:55296
	ds_read_b128 v[214:217], v163 offset:56320
	global_load_lds_dwordx4 v[178:179], off
	s_add_i32 m0, s90, 0x2000
	s_add_u32 s60, s60, 0x84000
	v_lshl_add_u64 v[178:179], s[70:71], 0, v[140:141]
	s_addc_u32 s61, s61, 0
	s_add_i32 s70, s91, s15
	global_load_lds_dwordx4 v[178:179], off
	v_lshl_add_u64 v[178:179], s[60:61], 0, v[138:139]
	s_mov_b32 m0, s70
	s_nop 0
	global_load_lds_dwordx4 v[178:179], off
	v_lshl_add_u64 v[178:179], s[60:61], 0, v[140:141]
	s_add_i32 m0, s70, 0x2000
	s_nop 0
	global_load_lds_dwordx4 v[178:179], off
	v_lshl_add_u64 v[178:179], s[58:59], 0, v[138:139]
	s_mov_b32 m0, s79
	s_nop 0
	global_load_lds_dwordx4 v[178:179], off
	v_lshl_add_u64 v[178:179], s[58:59], 0, v[140:141]
	s_mov_b32 m0, s80
	s_nop 0
	global_load_lds_dwordx4 v[178:179], off
	s_waitcnt vmcnt(8)
	s_waitcnt lgkmcnt(0)
	s_barrier
	s_setprio 1
	s_waitcnt lgkmcnt(0)
	v_mfma_f32_16x16x32_bf16 v[62:65], v[130:133], v[186:189], v[62:65]
	v_mfma_f32_16x16x32_bf16 v[58:61], v[152:155], v[186:189], v[58:61]
	v_mfma_f32_16x16x32_bf16 v[46:49], v[130:133], v[194:197], v[46:49]
	v_mfma_f32_16x16x32_bf16 v[42:45], v[152:155], v[194:197], v[42:45]
	v_mfma_f32_16x16x32_bf16 v[30:33], v[130:133], v[202:205], v[30:33]
	v_mfma_f32_16x16x32_bf16 v[26:29], v[152:155], v[202:205], v[26:29]
	v_mfma_f32_16x16x32_bf16 v[14:17], v[130:133], v[210:213], v[14:17]
	v_mfma_f32_16x16x32_bf16 v[10:13], v[152:155], v[210:213], v[10:13]
	v_mfma_f32_16x16x32_bf16 v[62:65], v[134:137], v[190:193], v[62:65]
	v_mfma_f32_16x16x32_bf16 v[58:61], v[156:159], v[190:193], v[58:61]
	v_mfma_f32_16x16x32_bf16 v[46:49], v[134:137], v[198:201], v[46:49]
	v_mfma_f32_16x16x32_bf16 v[42:45], v[156:159], v[198:201], v[42:45]
	v_mfma_f32_16x16x32_bf16 v[30:33], v[134:137], v[206:209], v[30:33]
	v_mfma_f32_16x16x32_bf16 v[26:29], v[156:159], v[206:209], v[26:29]
	v_mfma_f32_16x16x32_bf16 v[14:17], v[134:137], v[214:217], v[14:17]
	v_mfma_f32_16x16x32_bf16 v[10:13], v[156:159], v[214:217], v[10:13]
	s_setprio 0
	s_setprio 1
	v_mfma_f32_16x16x32_bf16 v[54:57], v[166:169], v[186:189], v[54:57]
	v_mfma_f32_16x16x32_bf16 v[50:53], v[174:177], v[186:189], v[50:53]
	v_mfma_f32_16x16x32_bf16 v[38:41], v[166:169], v[194:197], v[38:41]
	v_mfma_f32_16x16x32_bf16 v[34:37], v[174:177], v[194:197], v[34:37]
	v_mfma_f32_16x16x32_bf16 v[22:25], v[166:169], v[202:205], v[22:25]
	v_mfma_f32_16x16x32_bf16 v[18:21], v[174:177], v[202:205], v[18:21]
	v_mfma_f32_16x16x32_bf16 v[6:9], v[166:169], v[210:213], v[6:9]
	v_mfma_f32_16x16x32_bf16 v[2:5], v[174:177], v[210:213], v[2:5]
	v_mfma_f32_16x16x32_bf16 v[54:57], v[170:173], v[190:193], v[54:57]
	v_mfma_f32_16x16x32_bf16 v[50:53], v[182:185], v[190:193], v[50:53]
	v_mfma_f32_16x16x32_bf16 v[38:41], v[170:173], v[198:201], v[38:41]
	v_mfma_f32_16x16x32_bf16 v[34:37], v[182:185], v[198:201], v[34:37]
	v_mfma_f32_16x16x32_bf16 v[22:25], v[170:173], v[206:209], v[22:25]
	v_mfma_f32_16x16x32_bf16 v[18:21], v[182:185], v[206:209], v[18:21]
	v_mfma_f32_16x16x32_bf16 v[6:9], v[170:173], v[214:217], v[6:9]
	v_mfma_f32_16x16x32_bf16 v[2:5], v[182:185], v[214:217], v[2:5]
	s_setprio 0
	s_barrier
	s_add_i32 s89, s89, 2
	s_add_u32 s56, s56, 0x8000
	s_addc_u32 s57, s57, 0
	s_add_u32 s87, s87, 0x8000
	s_addc_u32 s88, s88, 0
